# mixers queue order: latent Hyena items first, FNet GEMM tiles second, context Hyena items last (ticket remap)
# baseline (speedup 1.0000x reference)
; DI int TID() { int t = threadIdx.x; asm volatile("" : "+v"(t)); return t; }
; DI void hyena_item(const Params& p, int l, int it) {
;     ...
;   if (it < 2048) { c = it >> 3; f = l; L = 2048; posoff = CTXL; tt0 = (it & 7) * 256 + w * 64; ntile = 32; }
;   else { c = it - 2048; f = 2; L = 256; posoff = 0; tt0 = w * 64; ntile = 4; }
;   const u16* R0 = WSP(const u16, OFF_RF) + ((size_t)(f * 256 + c) * 2) * RSTR;
;   const u16* R1 = R0 + RSTR;
;   const u16* UT = WSP(const u16, OFF_UT);
;   const int l16 = lane & 15, kg = lane >> 4;
;   f32x4 acc[4];
; #pragma unroll
;   for (int i = 0; i < 4; ++i) acc[i] = (f32x4){0.f, 0.f, 0.f, 0.f};
;   const u16* ub = UT + ((size_t)(c * 16 + l16)) * TPB + posoff + kg * 8;
;   const u16* rsel = (l16 & 1) ? (R1 - 1) : R0;
;   const int nb = L - (tt0 + l16) + kg * 8;
;   for (int s0 = 0; s0 < L; s0 += 32) {
;     const bf16x8 bfrag = *(const bf16x8*)(ub + s0);
; #pragma unroll
;     for (int i = 0; i < 4; ++i) {
;       const u32* ap = (const u32*)(rsel + (nb - 16 * i + s0));
;       union { u32 u[4]; bf16x8 v; } au;
;       au.u[0] = ap[0]; au.u[1] = ap[1]; au.u[2] = ap[2]; au.u[3] = ap[3];
;       acc[i] = __builtin_amdgcn_mfma_f32_16x16x32_bf16(au.v, bfrag, acc[i], 0, 0, 0);
;     }
;   }
;     ...
;     if (TID() == 0) *sitem = atomicAdd(ctr, 1);
;     __syncthreads();
;     const int it = *sitem;
;     __syncthreads();
;     if (it >= nf + nh) break;
;     if (it < nf) fnet_item(p, it, smem);
;     else if (it - nf < 1024) hyena_item_lat(p, l, it - nf);
;     else hyena_item(p, l, it - nf + 1024);
.LBB0_1133:
	s_or_b64 exec, exec, s[34:35]
	v_readlane_b32 s13, v254, 1
	s_waitcnt lgkmcnt(0)
	s_barrier
	v_mov_b32_e32 v0, s13
	ds_read_b32 v0, v0
	s_mov_b64 s[34:35], -1
	s_waitcnt lgkmcnt(0)
	s_barrier
	v_cmp_le_i32_e32 vcc, s41, v0
	v_readfirstlane_b32 s45, v0
	s_cbranch_vccnz .LBB0_1128
	s_add_i32 s13, s40, 0x400
	s_cmp_ge_u32 s45, s13
	s_cbranch_scc1 .Lq_keep
	s_cmpk_lt_u32 s45, 0x400
	s_cbranch_scc1 .Lq_lat
	s_addk_i32 s45, 0xfc00
	s_branch .Lq_keep
.Lq_lat:
	s_add_i32 s45, s45, s40
.Lq_keep:
	s_cmp_ge_i32 s45, s40
	s_cbranch_scc0 .LBB0_1142
	s_sub_i32 s13, s45, s40
	s_cmpk_gt_i32 s13, 0x3ff
	s_cbranch_scc0 .LBB0_1137
	v_and_b32_e32 v17, 15, v218
	v_and_b32_e32 v16, 0xffffffc0, v218
	v_bfe_u32 v22, v218, 4, 2
	s_add_i32 s36, s13, 0xfffffc00
	s_add_i32 s38, s13, 0x400
	v_lshl_or_b32 v1, s36, 4, v17
	s_movk_i32 s16, 0x900
	s_mul_i32 s86, s38, 0x2020
	v_mul_lo_u32 v172, v1, s16
	v_readlane_b32 s16, v255, 50
	s_lshl_b64 s[34:35], s[86:87], 1
	v_readlane_b32 s17, v255, 51
	s_add_u32 s34, s96, s34
	s_addc_u32 s35, s97, s35
	s_nop 2
	v_lshl_add_u64 v[18:19], v[172:173], 1, s[16:17]
	v_lshlrev_b32_e32 v172, 4, v22
	v_lshl_add_u64 v[2:3], v[18:19], 0, v[172:173]
	v_bfe_i32 v0, v218, 0, 1
	v_and_b32_e32 v172, 0x201e, v0
	v_lshl_add_u64 v[0:1], s[34:35], 0, v[172:173]
	s_mov_b64 s[34:35], 0x199c8000
	v_lshl_add_u64 v[0:1], v[0:1], 0, s[34:35]
	v_lshlrev_b32_e32 v4, 3, v22
	v_sub_u32_e32 v4, v4, v16
	v_add_u32_e32 v4, 0x100, v4
	v_sub_u32_e32 v6, v4, v17
	v_ashrrev_i32_e32 v7, 31, v6
	v_lshl_add_u64 v[6:7], v[6:7], 1, v[0:1]
	global_load_dwordx4 v[32:35], v[6:7], off offset:-96
	global_load_dwordx4 v[36:39], v[6:7], off offset:-64
	global_load_dwordx4 v[40:43], v[6:7], off offset:-32
	global_load_dwordx4 v[44:47], v[6:7], off
	global_load_dwordx4 v[48:51], v[6:7], off offset:32
	global_load_dwordx4 v[52:55], v[6:7], off offset:64
	global_load_dwordx4 v[56:59], v[6:7], off offset:96
	global_load_dwordx4 v[60:63], v[6:7], off offset:128
	global_load_dwordx4 v[64:67], v[6:7], off offset:160
	global_load_dwordx4 v[68:71], v[6:7], off offset:192
	global_load_dwordx4 v[72:75], v[6:7], off offset:224
	global_load_dwordx4 v[76:79], v[6:7], off offset:256
	global_load_dwordx4 v[80:83], v[6:7], off offset:288
	global_load_dwordx4 v[84:87], v[6:7], off offset:320
	global_load_dwordx4 v[88:91], v[6:7], off offset:352
	global_load_dwordx4 v[92:95], v[6:7], off offset:384
	global_load_dwordx4 v[96:99], v[6:7], off offset:416
	global_load_dwordx4 v[100:103], v[6:7], off offset:448
	global_load_dwordx4 v[104:107], v[2:3], off
	global_load_dwordx4 v[108:111], v[2:3], off offset:64
	global_load_dwordx4 v[112:115], v[2:3], off offset:128
	global_load_dwordx4 v[116:119], v[2:3], off offset:192
	global_load_dwordx4 v[120:123], v[2:3], off offset:256
	global_load_dwordx4 v[124:127], v[2:3], off offset:320
	global_load_dwordx4 v[128:131], v[2:3], off offset:384
	global_load_dwordx4 v[132:135], v[2:3], off offset:448
	s_mov_b32 s39, s87
	s_lshl_b64 s[34:35], s[38:39], 2
	v_readlane_b32 s16, v254, 45
	v_readlane_b32 s17, v254, 46
	s_add_u32 s34, s16, s34
	s_addc_u32 s35, s17, s35
	v_mov_b32_e32 v149, 0xe000
	global_load_dword v144, v149, s[34:35]
	global_load_dword v145, v149, s[34:35] offset:1024
	global_load_dword v146, v149, s[34:35] offset:2048
	global_load_dword v147, v149, s[34:35] offset:3072
	s_add_i32 s86, s36, s42
	s_lshl_b64 s[34:35], s[86:87], 2
	v_readlane_b32 s18, v254, 31
	v_readlane_b32 s19, v254, 32
	s_add_u32 s34, s18, s34
	s_addc_u32 s35, s19, s35
	global_load_dword v148, v173, s[34:35]
	v_lshl_add_u32 v25, v22, 2, v16
	v_mov_b32_e32 v27, 0
	v_lshlrev_b32_e32 v26, 1, v25
	v_lshl_add_u64 v[28:29], v[18:19], 0, v[26:27]
	global_load_dwordx2 v[136:137], v[28:29], off
	global_load_dwordx2 v[138:139], v[28:29], off offset:32
	global_load_dwordx2 v[140:141], v[28:29], off offset:64
	global_load_dwordx2 v[142:143], v[28:29], off offset:96
	v_mov_b64_e32 v[0:1], 0
	v_mov_b64_e32 v[2:3], 0
	v_mov_b64_e32 v[4:5], 0
	v_mov_b64_e32 v[6:7], 0
	v_mov_b64_e32 v[8:9], 0
	v_mov_b64_e32 v[10:11], 0
	v_mov_b64_e32 v[12:13], 0
	v_mov_b64_e32 v[14:15], 0
	v_lshlrev_b32_e32 v30, 10, v17
	v_lshl_add_u32 v30, v25, 2, v30
	s_lshl_b32 s16, s36, 14
	s_add_u32 s16, s16, 0x2000000
	s_add_u32 s16, s96, s16
	s_addc_u32 s17, s97, 0
	s_waitcnt vmcnt(16)
	v_mfma_f32_16x16x32_bf16 v[0:3], v[44:47], v[104:107], v[0:3]
	v_mfma_f32_16x16x32_bf16 v[4:7], v[40:43], v[104:107], v[4:7]
	v_mfma_f32_16x16x32_bf16 v[8:11], v[36:39], v[104:107], v[8:11]
	v_mfma_f32_16x16x32_bf16 v[12:15], v[32:35], v[104:107], v[12:15]
	s_waitcnt vmcnt(15)
; DI u16 f2bf(float x) { u32 u = __float_as_uint(x); u += 0x7fffu + ((u >> 16) & 1u); return (u16)(u >> 16); }
; DI float bf2f(u16 v) { return __uint_as_float(((u32)v) << 16); }
; DI void hyena_item(const Params& p, int l, int it) {
;     ...
;   for (int s0 = 0; s0 < L; s0 += 32) {
;     const bf16x8 bfrag = *(const bf16x8*)(ub + s0);
; #pragma unroll
;     for (int i = 0; i < 4; ++i) {
;       const u32* ap = (const u32*)(rsel + (nb - 16 * i + s0));
;       union { u32 u[4]; bf16x8 v; } au;
;       au.u[0] = ap[0]; au.u[1] = ap[1]; au.u[2] = ap[2]; au.u[3] = ap[3];
;       acc[i] = __builtin_amdgcn_mfma_f32_16x16x32_bf16(au.v, bfrag, acc[i], 0, 0, 0);
;     }
;   }
;   float ssq = 0.f;
;   for (int t = 0; t < ntile; ++t) ssq += WSP(const float, OFF_PART)[(size_t)(f * 32 + t) * 256 + c];
;   const float scale = rsqrtf(ssq + EPSF);
;   const float bias = p.in[I_HYBIAS][l * 256 + c];
;   const u16* X1C = WSP(const u16, OFF_X1C);
;   u16* YM = WSP(u16, OFF_ACT);
;   const int b = l16;
; #pragma unroll
;   for (int i = 0; i < 4; ++i)
; #pragma unroll
;     for (int r = 0; r < 4; ++r) {
;       const int t = tt0 + 16 * i + kg * 4 + r;
;       const size_t row = (size_t)b * TPB + posoff + t;
;       const float u = bf2f(UT[((size_t)(c * 16 + b)) * TPB + posoff + t]);
;       const float x1 = bf2f(X1C[row * 256 + c]);
;       YM[row * 1024 + c] = f2bf(x1 * (scale * acc[i][r] + bias * u));
	v_mfma_f32_16x16x32_bf16 v[0:3], v[52:55], v[108:111], v[0:3]
	v_mfma_f32_16x16x32_bf16 v[4:7], v[48:51], v[108:111], v[4:7]
	v_mfma_f32_16x16x32_bf16 v[8:11], v[44:47], v[108:111], v[8:11]
	v_mfma_f32_16x16x32_bf16 v[12:15], v[40:43], v[108:111], v[12:15]
	s_waitcnt vmcnt(14)
	v_mfma_f32_16x16x32_bf16 v[0:3], v[60:63], v[112:115], v[0:3]
	v_mfma_f32_16x16x32_bf16 v[4:7], v[56:59], v[112:115], v[4:7]
	v_mfma_f32_16x16x32_bf16 v[8:11], v[52:55], v[112:115], v[8:11]
	v_mfma_f32_16x16x32_bf16 v[12:15], v[48:51], v[112:115], v[12:15]
	s_waitcnt vmcnt(13)
	v_mfma_f32_16x16x32_bf16 v[0:3], v[68:71], v[116:119], v[0:3]
	v_mfma_f32_16x16x32_bf16 v[4:7], v[64:67], v[116:119], v[4:7]
	v_mfma_f32_16x16x32_bf16 v[8:11], v[60:63], v[116:119], v[8:11]
	v_mfma_f32_16x16x32_bf16 v[12:15], v[56:59], v[116:119], v[12:15]
	s_waitcnt vmcnt(12)
	v_mfma_f32_16x16x32_bf16 v[0:3], v[76:79], v[120:123], v[0:3]
	v_mfma_f32_16x16x32_bf16 v[4:7], v[72:75], v[120:123], v[4:7]
	v_mfma_f32_16x16x32_bf16 v[8:11], v[68:71], v[120:123], v[8:11]
	v_mfma_f32_16x16x32_bf16 v[12:15], v[64:67], v[120:123], v[12:15]
	s_waitcnt vmcnt(11)
	v_mfma_f32_16x16x32_bf16 v[0:3], v[84:87], v[124:127], v[0:3]
	v_mfma_f32_16x16x32_bf16 v[4:7], v[80:83], v[124:127], v[4:7]
	v_mfma_f32_16x16x32_bf16 v[8:11], v[76:79], v[124:127], v[8:11]
	v_mfma_f32_16x16x32_bf16 v[12:15], v[72:75], v[124:127], v[12:15]
	s_waitcnt vmcnt(10)
	v_mfma_f32_16x16x32_bf16 v[0:3], v[92:95], v[128:131], v[0:3]
	v_mfma_f32_16x16x32_bf16 v[4:7], v[88:91], v[128:131], v[4:7]
	v_mfma_f32_16x16x32_bf16 v[8:11], v[84:87], v[128:131], v[8:11]
	v_mfma_f32_16x16x32_bf16 v[12:15], v[80:83], v[128:131], v[12:15]
	s_waitcnt vmcnt(9)
	v_mfma_f32_16x16x32_bf16 v[0:3], v[100:103], v[132:135], v[0:3]
	v_mfma_f32_16x16x32_bf16 v[4:7], v[96:99], v[132:135], v[4:7]
	v_mfma_f32_16x16x32_bf16 v[8:11], v[92:95], v[132:135], v[8:11]
	v_mfma_f32_16x16x32_bf16 v[12:15], v[88:91], v[132:135], v[12:15]
	s_waitcnt vmcnt(0)
	v_add_f32_e32 v20, 0, v144
	v_add_f32_e32 v20, v20, v145
	v_add_f32_e32 v20, v20, v146
	v_add_f32_e32 v20, v20, v147
	s_mov_b32 s18, 0x800000
	v_add_f32_e32 v20, 0x358637bd, v20
	v_cmp_gt_f32_e32 vcc, s18, v20
	v_mul_f32_e32 v21, 0x4b800000, v20
	s_nop 1
	v_cndmask_b32_e32 v20, v20, v21, vcc
	v_rsq_f32_e32 v20, v20
	s_nop 0
	v_mul_f32_e32 v21, 0x45800000, v20
	v_cndmask_b32_e32 v20, v20, v21, vcc
	s_nop 4
	v_lshlrev_b32_e32 v21, 16, v136
	v_mul_f32_e32 v21, v148, v21
	v_fmac_f32_e32 v21, v0, v20
	v_mov_b32_e32 v0, v21
	v_and_b32_e32 v21, 0xffff0000, v136
	v_mul_f32_e32 v21, v148, v21
	v_fmac_f32_e32 v21, v1, v20
	v_mov_b32_e32 v1, v21
	v_lshlrev_b32_e32 v21, 16, v137
	v_mul_f32_e32 v21, v148, v21
	v_fmac_f32_e32 v21, v2, v20
	v_mov_b32_e32 v2, v21
	v_and_b32_e32 v21, 0xffff0000, v137
	v_mul_f32_e32 v21, v148, v21
	v_fmac_f32_e32 v21, v3, v20
	v_mov_b32_e32 v3, v21
	v_lshlrev_b32_e32 v21, 16, v138
	v_mul_f32_e32 v21, v148, v21
	v_fmac_f32_e32 v21, v4, v20
	v_mov_b32_e32 v4, v21
	v_and_b32_e32 v21, 0xffff0000, v138
	v_mul_f32_e32 v21, v148, v21
	v_fmac_f32_e32 v21, v5, v20
	v_mov_b32_e32 v5, v21
	v_lshlrev_b32_e32 v21, 16, v139
	v_mul_f32_e32 v21, v148, v21
	v_fmac_f32_e32 v21, v6, v20
	v_mov_b32_e32 v6, v21
	v_and_b32_e32 v21, 0xffff0000, v139
	v_mul_f32_e32 v21, v148, v21
	v_fmac_f32_e32 v21, v7, v20
	v_mov_b32_e32 v7, v21
	v_lshlrev_b32_e32 v21, 16, v140
	v_mul_f32_e32 v21, v148, v21
	v_fmac_f32_e32 v21, v8, v20
	v_mov_b32_e32 v8, v21
	v_and_b32_e32 v21, 0xffff0000, v140
	v_mul_f32_e32 v21, v148, v21
	v_fmac_f32_e32 v21, v9, v20
	v_mov_b32_e32 v9, v21
	v_lshlrev_b32_e32 v21, 16, v141
	v_mul_f32_e32 v21, v148, v21
	v_fmac_f32_e32 v21, v10, v20
	v_mov_b32_e32 v10, v21
	v_and_b32_e32 v21, 0xffff0000, v141
	v_mul_f32_e32 v21, v148, v21
	v_fmac_f32_e32 v21, v11, v20
	v_mov_b32_e32 v11, v21
	v_lshlrev_b32_e32 v21, 16, v142
	v_mul_f32_e32 v21, v148, v21
	v_fmac_f32_e32 v21, v12, v20
	v_mov_b32_e32 v12, v21
	v_and_b32_e32 v21, 0xffff0000, v142
	v_mul_f32_e32 v21, v148, v21
	v_fmac_f32_e32 v21, v13, v20
	v_mov_b32_e32 v13, v21
	v_lshlrev_b32_e32 v21, 16, v143
	v_mul_f32_e32 v21, v148, v21
	v_fmac_f32_e32 v21, v14, v20
	v_mov_b32_e32 v14, v21
	v_and_b32_e32 v21, 0xffff0000, v143
	v_mul_f32_e32 v21, v148, v21
	v_fmac_f32_e32 v21, v15, v20
	v_mov_b32_e32 v15, v21
	global_store_dwordx4 v30, v[0:3], s[16:17]
	global_store_dwordx4 v30, v[4:7], s[16:17] offset:64
	global_store_dwordx4 v30, v[8:11], s[16:17] offset:128
	global_store_dwordx4 v30, v[12:15], s[16:17] offset:192
	s_mov_b32 s24, s64
	v_readlane_b32 s18, v254, 10
	v_readlane_b32 s19, v254, 11
	s_mov_b64 s[34:35], 0
